# LayerNorm row loops: all four row loads issued up front (one memory round trip per row instead of two), first partial sum on renamed temporaries
# speedup vs baseline: 1.0037x; 1.0037x over previous
; template <bool FINAL>
; DI void phase_ln(float* y, bf16_t* xb, float* stats, const float* g, const float* b, const int tid) {
;     ...
;     for (int row = blockIdx.x * 8 + wid; row < MTOK; row += gridDim.x * 8) {
;         float* yp = y + (size_t)row * 1024;
;         f32x4 v[4]; float s = 0.f;
; #pragma unroll
;         for (int k = 0; k < 4; ++k) { v[k] = __builtin_nontemporal_load((const f32x4*)(yp + k * 256 + lane * 4)); s += v[k][0] + v[k][1] + v[k][2] + v[k][3]; }
;         const float mean = wave_sum(s) * (1.0f / 1024.0f);
;         float q = 0.f;
; #pragma unroll
;         for (int k = 0; k < 4; ++k) { v[k] = v[k] - mean; q += v[k][0] * v[k][0] + v[k][1] * v[k][1] + v[k][2] * v[k][2] + v[k][3] * v[k][3]; }
;         const float var = wave_sum(q) * (1.0f / 1024.0f);
;         const float rs = 1.0f / sqrtf(var + 1e-5f);
;         if (!FINAL && lane == 0) { f32x2 sm = {mean, rs}; *(f32x2*)(stats + 2 * (size_t)row) = sm; }
.LBB0_90:
	v_ashrrev_i32_e32 v51, 31, v50
	v_lshlrev_b64 v[34:35], 12, v[50:51]
	v_lshl_add_u64 v[42:43], v[52:53], 0, v[34:35]
	global_load_dwordx4 v[38:41], v[42:43], off nt
	global_load_dwordx4 v[34:37], v[42:43], off offset:1024 nt
	global_load_dwordx4 v[46:49], v[42:43], off offset:2048 nt
	s_nop 0
	global_load_dwordx4 v[42:45], v[42:43], off offset:3072 nt
	s_mov_b32 s2, 0xf800000
	s_waitcnt vmcnt(2)
	v_mov_b32_e32 v62, v38
	v_mov_b32_e32 v63, v34
	v_mov_b32_e32 v64, v39
	v_mov_b32_e32 v65, v35
	v_pk_add_f32 v[62:63], v[62:63], v[64:65]
	v_mov_b32_e32 v64, v40
	v_mov_b32_e32 v65, v36
	v_pk_add_f32 v[62:63], v[64:65], v[62:63]
	v_mov_b32_e32 v64, v41
	v_mov_b32_e32 v65, v37
	v_pk_add_f32 v[62:63], v[64:65], v[62:63]
	s_nop 0
	v_add_f32_e32 v0, 0, v62
	v_add_f32_e32 v0, v0, v63
	s_waitcnt vmcnt(0)
	v_mov_b32_e32 v62, v46
	v_mov_b32_e32 v63, v42
	v_mov_b32_e32 v64, v47
	v_mov_b32_e32 v65, v43
	v_pk_add_f32 v[62:63], v[62:63], v[64:65]
	v_mov_b32_e32 v64, v48
	v_mov_b32_e32 v65, v44
	v_pk_add_f32 v[62:63], v[64:65], v[62:63]
	v_mov_b32_e32 v64, v49
	v_mov_b32_e32 v65, v45
	v_pk_add_f32 v[62:63], v[64:65], v[62:63]
	s_nop 0
	v_add_f32_e32 v0, v0, v62
	v_add_f32_e32 v0, v0, v63
	ds_bpermute_b32 v62, v56, v0
	s_waitcnt lgkmcnt(0)
	v_add_f32_e32 v0, v0, v62
	ds_bpermute_b32 v62, v57, v0
	s_waitcnt lgkmcnt(0)
	v_add_f32_e32 v0, v0, v62
	ds_bpermute_b32 v62, v58, v0
	s_waitcnt lgkmcnt(0)
	v_add_f32_e32 v0, v0, v62
	ds_bpermute_b32 v62, v59, v0
	s_waitcnt lgkmcnt(0)
	v_add_f32_e32 v0, v0, v62
	ds_bpermute_b32 v62, v60, v0
	s_waitcnt lgkmcnt(0)
	v_add_f32_e32 v0, v0, v62
	ds_bpermute_b32 v62, v61, v0
	s_waitcnt lgkmcnt(0)
	v_add_f32_e32 v62, v0, v62
	v_fmamk_f32 v39, v62, 0xba800000, v39
	v_fmamk_f32 v35, v62, 0xba800000, v35
	v_fmac_f32_e32 v38, 0xba800000, v62
	v_mul_f32_e32 v0, v39, v39
	v_fmac_f32_e32 v34, 0xba800000, v62
	v_mul_f32_e32 v63, v35, v35
	v_fmamk_f32 v40, v62, 0xba800000, v40
	v_fmac_f32_e32 v0, v38, v38
	v_fmamk_f32 v36, v62, 0xba800000, v36
	v_fmac_f32_e32 v63, v34, v34
	v_fmamk_f32 v41, v62, 0xba800000, v41
	v_fmac_f32_e32 v0, v40, v40
	v_fmamk_f32 v37, v62, 0xba800000, v37
	v_fmac_f32_e32 v63, v36, v36
	v_fmac_f32_e32 v0, v41, v41
	v_fmac_f32_e32 v63, v37, v37
	v_fmamk_f32 v47, v62, 0xba800000, v47
	v_add_f32_e32 v0, v0, v63
	v_fmac_f32_e32 v46, 0xba800000, v62
	v_mul_f32_e32 v63, v47, v47
	v_fmamk_f32 v48, v62, 0xba800000, v48
	v_fmac_f32_e32 v63, v46, v46
	v_fmamk_f32 v49, v62, 0xba800000, v49
	v_fmac_f32_e32 v63, v48, v48
	v_fmac_f32_e32 v63, v49, v49
	v_fmamk_f32 v43, v62, 0xba800000, v43
	v_add_f32_e32 v0, v63, v0
	v_fmac_f32_e32 v42, 0xba800000, v62
	v_mul_f32_e32 v63, v43, v43
	v_fmamk_f32 v44, v62, 0xba800000, v44
	v_fmac_f32_e32 v63, v42, v42
	v_fmamk_f32 v45, v62, 0xba800000, v45
	v_fmac_f32_e32 v63, v44, v44
	v_fmac_f32_e32 v63, v45, v45
	v_add_f32_e32 v0, v63, v0
	ds_bpermute_b32 v63, v56, v0
	s_waitcnt lgkmcnt(0)
	v_add_f32_e32 v0, v0, v63
	ds_bpermute_b32 v63, v57, v0
	s_waitcnt lgkmcnt(0)
	v_add_f32_e32 v0, v0, v63
	ds_bpermute_b32 v63, v58, v0
	s_waitcnt lgkmcnt(0)
	v_add_f32_e32 v0, v0, v63
	ds_bpermute_b32 v63, v59, v0
	s_waitcnt lgkmcnt(0)
	v_add_f32_e32 v0, v0, v63
	ds_bpermute_b32 v63, v60, v0
	s_waitcnt lgkmcnt(0)
	v_add_f32_e32 v0, v0, v63
	ds_bpermute_b32 v63, v61, v0
	s_waitcnt lgkmcnt(0)
	v_add_f32_e32 v0, v0, v63
	v_fmamk_f32 v0, v0, 0x3a800000, v235
	v_cmp_gt_f32_e32 vcc, s2, v0
	v_mul_f32_e32 v63, 0x4f800000, v0
	s_nop 0
	v_cndmask_b32_e32 v0, v0, v63, vcc
	v_sqrt_f32_e32 v63, v0
	s_nop 0
	v_add_u32_e32 v64, -1, v63
	v_fma_f32 v65, -v64, v63, v0
	v_cmp_ge_f32_e64 s[4:5], 0, v65
	v_add_u32_e32 v65, 1, v63
	s_nop 0
	v_cndmask_b32_e64 v64, v63, v64, s[4:5]
	v_fma_f32 v63, -v65, v63, v0
	v_cmp_lt_f32_e64 s[4:5], 0, v63
	s_nop 1
	v_cndmask_b32_e64 v63, v64, v65, s[4:5]
	v_mul_f32_e32 v64, 0x37800000, v63
	v_cndmask_b32_e32 v63, v63, v64, vcc
	v_cmp_class_f32_e32 vcc, v0, v236
	s_nop 1
	v_cndmask_b32_e32 v0, v63, v0, vcc
	v_div_scale_f32 v63, s[4:5], v0, v0, 1.0
	v_rcp_f32_e32 v64, v63
	s_nop 0
	v_fma_f32 v65, -v63, v64, 1.0
	v_fmac_f32_e32 v64, v65, v64
	v_div_scale_f32 v65, vcc, 1.0, v0, 1.0
	v_mul_f32_e32 v66, v65, v64
	v_fma_f32 v67, -v63, v66, v65
	v_fmac_f32_e32 v66, v67, v64
	v_fma_f32 v63, -v63, v66, v65
	v_div_fmas_f32 v63, v63, v64, v66
	v_div_fixup_f32 v0, v63, v0, 1.0
	s_and_saveexec_b64 s[4:5], s[0:1]
	s_cbranch_execz .LBB0_89
	v_readlane_b32 s42, v251, 1
	v_readlane_b32 s43, v251, 2
	v_mul_f32_e32 v62, 0x3a800000, v62
	v_mov_b32_e32 v63, v0
	v_lshl_add_u64 v[64:65], v[50:51], 3, s[42:43]
	global_store_dwordx2 v[64:65], v[62:63], off
	s_branch .LBB0_89

; DI unsigned pk2(float lo, float hi) { f32x2 v = {lo, hi}; bf2_t b = __builtin_convertvector(v, bf2_t); return __builtin_bit_cast(unsigned, b); }
; template <bool FINAL>
; DI void phase_ln(float* y, bf16_t* xb, float* stats, const float* g, const float* b, const int tid) {
;     ...
;     for (int row = blockIdx.x * 8 + wid; row < MTOK; row += gridDim.x * 8) {
;         float* yp = y + (size_t)row * 1024;
;         f32x4 v[4]; float s = 0.f;
; #pragma unroll
;         for (int k = 0; k < 4; ++k) { v[k] = __builtin_nontemporal_load((const f32x4*)(yp + k * 256 + lane * 4)); s += v[k][0] + v[k][1] + v[k][2] + v[k][3]; }
;         const float mean = wave_sum(s) * (1.0f / 1024.0f);
;         float q = 0.f;
; #pragma unroll
;         for (int k = 0; k < 4; ++k) { v[k] = v[k] - mean; q += v[k][0] * v[k][0] + v[k][1] * v[k][1] + v[k][2] * v[k][2] + v[k][3] * v[k][3]; }
;         const float var = wave_sum(q) * (1.0f / 1024.0f);
;         const float rs = 1.0f / sqrtf(var + 1e-5f);
;         if (!FINAL && lane == 0) { f32x2 sm = {mean, rs}; *(f32x2*)(stats + 2 * (size_t)row) = sm; }
; #pragma unroll
;         for (int k = 0; k < 4; ++k) { const f32x4 o = v[k] * rs * gv[k] + bv[k];
;             if (FINAL) *(f32x4*)(yp + k * 256 + lane * 4) = o;
;             else { u32x2 w; w.x = pk2(o[0], o[1]); w.y = pk2(o[2], o[3]); *(u32x2*)(xb + (size_t)row * 1024 + k * 256 + lane * 4) = w; } }
.LBB0_538:
	v_ashrrev_i32_e32 v55, 31, v54
	v_lshlrev_b64 v[34:35], 12, v[54:55]
	v_lshl_add_u64 v[56:57], v[52:53], 0, v[34:35]
	global_load_dwordx4 v[38:41], v[56:57], off nt
	global_load_dwordx4 v[34:37], v[56:57], off offset:1024 nt
	global_load_dwordx4 v[46:49], v[56:57], off offset:2048 nt
	global_load_dwordx4 v[42:45], v[56:57], off offset:3072 nt
	v_add_u32_e32 v54, s9, v54
	s_waitcnt vmcnt(2)
	v_mov_b32_e32 v64, v38
	v_mov_b32_e32 v65, v34
	v_mov_b32_e32 v66, v39
	v_mov_b32_e32 v67, v35
	v_pk_add_f32 v[64:65], v[64:65], v[66:67]
	v_mov_b32_e32 v66, v40
	v_mov_b32_e32 v67, v36
	v_pk_add_f32 v[64:65], v[66:67], v[64:65]
	v_mov_b32_e32 v66, v41
	v_mov_b32_e32 v67, v37
	v_pk_add_f32 v[64:65], v[66:67], v[64:65]
	s_nop 0
	v_add_f32_e32 v0, 0, v64
	v_add_f32_e32 v0, v0, v65
	s_waitcnt vmcnt(0)
	v_mov_b32_e32 v64, v46
	v_mov_b32_e32 v65, v42
	v_mov_b32_e32 v66, v47
	v_mov_b32_e32 v67, v43
	v_pk_add_f32 v[64:65], v[64:65], v[66:67]
	v_mov_b32_e32 v66, v48
	v_mov_b32_e32 v67, v44
	v_pk_add_f32 v[64:65], v[66:67], v[64:65]
	v_mov_b32_e32 v66, v49
	v_mov_b32_e32 v67, v45
	v_pk_add_f32 v[64:65], v[66:67], v[64:65]
	s_nop 0
	v_add_f32_e32 v0, v0, v64
	v_add_f32_e32 v0, v0, v65
	ds_bpermute_b32 v55, v51, v0
	s_waitcnt lgkmcnt(0)
	v_add_f32_e32 v0, v0, v55
	ds_bpermute_b32 v55, v58, v0
	s_waitcnt lgkmcnt(0)
	v_add_f32_e32 v0, v0, v55
	ds_bpermute_b32 v55, v59, v0
	s_waitcnt lgkmcnt(0)
	v_add_f32_e32 v0, v0, v55
	ds_bpermute_b32 v55, v60, v0
	s_waitcnt lgkmcnt(0)
	v_add_f32_e32 v0, v0, v55
	ds_bpermute_b32 v55, v61, v0
	s_waitcnt lgkmcnt(0)
	v_add_f32_e32 v0, v0, v55
	ds_bpermute_b32 v55, v62, v0
	s_waitcnt lgkmcnt(0)
	v_add_f32_e32 v0, v0, v55
	v_fmac_f32_e32 v39, 0xba800000, v0
	v_fmac_f32_e32 v35, 0xba800000, v0
	v_fmamk_f32 v38, v0, 0xba800000, v38
	v_mul_f32_e32 v55, v39, v39
	v_fmamk_f32 v64, v0, 0xba800000, v36
	v_fmamk_f32 v34, v0, 0xba800000, v34
	v_mul_f32_e32 v36, v35, v35
	v_fmamk_f32 v40, v0, 0xba800000, v40
	v_fmac_f32_e32 v55, v38, v38
	v_fmac_f32_e32 v36, v34, v34
	v_fmamk_f32 v41, v0, 0xba800000, v41
	v_fmac_f32_e32 v55, v40, v40
	v_fmamk_f32 v65, v0, 0xba800000, v37
	v_fmac_f32_e32 v36, v64, v64
	v_fmamk_f32 v47, v0, 0xba800000, v47
	v_fmamk_f32 v43, v0, 0xba800000, v43
	v_fmac_f32_e32 v55, v41, v41
	v_fmac_f32_e32 v36, v65, v65
	v_fmac_f32_e32 v46, 0xba800000, v0
	v_fmac_f32_e32 v42, 0xba800000, v0
	v_mov_b32_e32 v66, v43
	v_mov_b32_e32 v67, v47
	v_add_f32_e32 v55, v55, v36
	v_fmamk_f32 v48, v0, 0xba800000, v48
	v_fmamk_f32 v44, v0, 0xba800000, v44
	v_mov_b32_e32 v36, v42
	v_mov_b32_e32 v37, v46
	v_pk_mul_f32 v[66:67], v[66:67], v[66:67]
	v_fmamk_f32 v49, v0, 0xba800000, v49
	v_fmamk_f32 v45, v0, 0xba800000, v45
	v_pk_fma_f32 v[36:37], v[36:37], v[36:37], v[66:67]
	v_mov_b32_e32 v66, v44
	v_mov_b32_e32 v67, v48
	v_pk_fma_f32 v[36:37], v[66:67], v[66:67], v[36:37]
	v_mov_b32_e32 v66, v45
	v_mov_b32_e32 v67, v49
	v_pk_fma_f32 v[36:37], v[66:67], v[66:67], v[36:37]
	s_nop 0
	v_add_f32_e32 v0, v37, v55
	v_add_f32_e32 v0, v36, v0
	ds_bpermute_b32 v36, v51, v0
	s_waitcnt lgkmcnt(0)
	v_add_f32_e32 v0, v0, v36
	ds_bpermute_b32 v36, v58, v0
	s_waitcnt lgkmcnt(0)
	v_add_f32_e32 v0, v0, v36
	ds_bpermute_b32 v36, v59, v0
	s_waitcnt lgkmcnt(0)
	v_add_f32_e32 v0, v0, v36
	ds_bpermute_b32 v36, v60, v0
	s_waitcnt lgkmcnt(0)
	v_add_f32_e32 v0, v0, v36
	ds_bpermute_b32 v36, v61, v0
	s_waitcnt lgkmcnt(0)
	v_add_f32_e32 v0, v0, v36
	ds_bpermute_b32 v36, v62, v0
	s_waitcnt lgkmcnt(0)
	v_add_f32_e32 v0, v0, v36
	v_fmamk_f32 v0, v0, 0x3a800000, v235
	v_cmp_gt_f32_e32 vcc, s2, v0
	v_mul_f32_e32 v36, 0x4f800000, v0
	s_nop 0
	v_cndmask_b32_e32 v0, v0, v36, vcc
	v_sqrt_f32_e32 v36, v0
	s_nop 0
	v_add_u32_e32 v37, -1, v36
	v_fma_f32 v55, -v37, v36, v0
	v_cmp_ge_f32_e64 s[0:1], 0, v55
	v_add_u32_e32 v55, 1, v36
	s_nop 0
	v_cndmask_b32_e64 v37, v36, v37, s[0:1]
	v_fma_f32 v36, -v55, v36, v0
	v_cmp_lt_f32_e64 s[0:1], 0, v36
	s_nop 1
	v_cndmask_b32_e64 v36, v37, v55, s[0:1]
	v_mul_f32_e32 v37, 0x37800000, v36
	v_cndmask_b32_e32 v36, v36, v37, vcc
	v_cmp_class_f32_e32 vcc, v0, v236
	s_nop 1
	v_cndmask_b32_e32 v0, v36, v0, vcc
	v_div_scale_f32 v36, s[0:1], v0, v0, 1.0
	v_rcp_f32_e32 v37, v36
	s_nop 0
	v_fma_f32 v55, -v36, v37, 1.0
	v_fmac_f32_e32 v37, v55, v37
	v_div_scale_f32 v55, vcc, 1.0, v0, 1.0
	v_mul_f32_e32 v63, v55, v37
	v_fma_f32 v66, -v36, v63, v55
	v_fmac_f32_e32 v63, v66, v37
	v_fma_f32 v36, -v36, v63, v55
	v_div_fmas_f32 v36, v36, v37, v63
	v_div_fixup_f32 v0, v36, v0, 1.0
	v_pk_mul_f32 v[36:37], v[38:39], v[0:1] op_sel_hi:[1,0]
	v_pk_mul_f32 v[38:39], v[40:41], v[0:1] op_sel_hi:[1,0]
	v_pk_fma_f32 v[36:37], v[2:3], v[36:37], v[10:11]
	v_pk_fma_f32 v[38:39], v[4:5], v[38:39], v[12:13]
	global_store_dwordx4 v[56:57], v[36:39], off
	v_pk_mul_f32 v[34:35], v[34:35], v[0:1] op_sel_hi:[1,0]
	v_cmp_lt_i32_e32 vcc, s8, v54
	v_pk_mul_f32 v[36:37], v[64:65], v[0:1] op_sel_hi:[1,0]
	v_pk_fma_f32 v[34:35], v[6:7], v[34:35], v[14:15]
	v_pk_fma_f32 v[36:37], v[8:9], v[36:37], v[16:17]
	global_store_dwordx4 v[56:57], v[34:37], off offset:1024
	s_or_b64 s[6:7], vcc, s[6:7]
	s_nop 0
	v_pk_mul_f32 v[34:35], v[46:47], v[0:1] op_sel_hi:[1,0]
	v_pk_mul_f32 v[36:37], v[48:49], v[0:1] op_sel_hi:[1,0]
	v_pk_fma_f32 v[34:35], v[18:19], v[34:35], v[26:27]
	v_pk_fma_f32 v[36:37], v[20:21], v[36:37], v[28:29]
	global_store_dwordx4 v[56:57], v[34:37], off offset:2048
	s_nop 1
	v_pk_mul_f32 v[34:35], v[42:43], v[0:1] op_sel_hi:[1,0]
	v_pk_mul_f32 v[36:37], v[44:45], v[0:1] op_sel_hi:[1,0]
	v_pk_fma_f32 v[34:35], v[22:23], v[34:35], v[30:31]
	v_pk_fma_f32 v[36:37], v[24:25], v[36:37], v[32:33]
	global_store_dwordx4 v[56:57], v[34:37], off offset:3072
	s_andn2_b64 exec, exec, s[6:7]
	s_cbranch_execnz .LBB0_538

; template <bool FINAL>
; DI void phase_ln(float* y, bf16_t* xb, float* stats, const float* g, const float* b, const int tid) {
;     ...
;     for (int row = blockIdx.x * 8 + wid; row < MTOK; row += gridDim.x * 8) {
;         float* yp = y + (size_t)row * 1024;
;         f32x4 v[4]; float s = 0.f;
; #pragma unroll
;         for (int k = 0; k < 4; ++k) { v[k] = __builtin_nontemporal_load((const f32x4*)(yp + k * 256 + lane * 4)); s += v[k][0] + v[k][1] + v[k][2] + v[k][3]; }
;         const float mean = wave_sum(s) * (1.0f / 1024.0f);
;         float q = 0.f;
; #pragma unroll
;         for (int k = 0; k < 4; ++k) { v[k] = v[k] - mean; q += v[k][0] * v[k][0] + v[k][1] * v[k][1] + v[k][2] * v[k][2] + v[k][3] * v[k][3]; }
;         const float var = wave_sum(q) * (1.0f / 1024.0f);
;         const float rs = 1.0f / sqrtf(var + 1e-5f);
;         if (!FINAL && lane == 0) { f32x2 sm = {mean, rs}; *(f32x2*)(stats + 2 * (size_t)row) = sm; }
.LBB0_544:
	v_ashrrev_i32_e32 v51, 31, v50
	v_lshlrev_b64 v[34:35], 12, v[50:51]
	v_lshl_add_u64 v[42:43], v[52:53], 0, v[34:35]
	global_load_dwordx4 v[38:41], v[42:43], off nt
	global_load_dwordx4 v[34:37], v[42:43], off offset:1024 nt
	global_load_dwordx4 v[46:49], v[42:43], off offset:2048 nt
	s_nop 0
	global_load_dwordx4 v[42:45], v[42:43], off offset:3072 nt
	s_mov_b32 s2, 0xf800000
	s_waitcnt vmcnt(2)
	v_mov_b32_e32 v62, v38
	v_mov_b32_e32 v63, v34
	v_mov_b32_e32 v64, v39
	v_mov_b32_e32 v65, v35
	v_pk_add_f32 v[62:63], v[62:63], v[64:65]
	v_mov_b32_e32 v64, v40
	v_mov_b32_e32 v65, v36
	v_pk_add_f32 v[62:63], v[64:65], v[62:63]
	v_mov_b32_e32 v64, v41
	v_mov_b32_e32 v65, v37
	v_pk_add_f32 v[62:63], v[64:65], v[62:63]
	s_nop 0
	v_add_f32_e32 v0, 0, v62
	v_add_f32_e32 v0, v0, v63
	s_waitcnt vmcnt(0)
	v_mov_b32_e32 v62, v46
	v_mov_b32_e32 v63, v42
	v_mov_b32_e32 v64, v47
	v_mov_b32_e32 v65, v43
	v_pk_add_f32 v[62:63], v[62:63], v[64:65]
	v_mov_b32_e32 v64, v48
	v_mov_b32_e32 v65, v44
	v_pk_add_f32 v[62:63], v[64:65], v[62:63]
	v_mov_b32_e32 v64, v49
	v_mov_b32_e32 v65, v45
	v_pk_add_f32 v[62:63], v[64:65], v[62:63]
	s_nop 0
	v_add_f32_e32 v0, v0, v62
	v_add_f32_e32 v0, v0, v63
	ds_bpermute_b32 v62, v56, v0
	s_waitcnt lgkmcnt(0)
	v_add_f32_e32 v0, v0, v62
	ds_bpermute_b32 v62, v57, v0
	s_waitcnt lgkmcnt(0)
	v_add_f32_e32 v0, v0, v62
	ds_bpermute_b32 v62, v58, v0
	s_waitcnt lgkmcnt(0)
	v_add_f32_e32 v0, v0, v62
	ds_bpermute_b32 v62, v59, v0
	s_waitcnt lgkmcnt(0)
	v_add_f32_e32 v0, v0, v62
	ds_bpermute_b32 v62, v60, v0
	s_waitcnt lgkmcnt(0)
	v_add_f32_e32 v0, v0, v62
	ds_bpermute_b32 v62, v61, v0
	s_waitcnt lgkmcnt(0)
	v_add_f32_e32 v62, v0, v62
	v_fmamk_f32 v39, v62, 0xba800000, v39
	v_fmamk_f32 v35, v62, 0xba800000, v35
	v_fmac_f32_e32 v38, 0xba800000, v62
	v_mul_f32_e32 v0, v39, v39
	v_fmac_f32_e32 v34, 0xba800000, v62
	v_mul_f32_e32 v63, v35, v35
	v_fmamk_f32 v40, v62, 0xba800000, v40
	v_fmac_f32_e32 v0, v38, v38
	v_fmamk_f32 v36, v62, 0xba800000, v36
	v_fmac_f32_e32 v63, v34, v34
	v_fmamk_f32 v41, v62, 0xba800000, v41
	v_fmac_f32_e32 v0, v40, v40
	v_fmamk_f32 v37, v62, 0xba800000, v37
	v_fmac_f32_e32 v63, v36, v36
	v_fmac_f32_e32 v0, v41, v41
	v_fmac_f32_e32 v63, v37, v37
	v_fmamk_f32 v47, v62, 0xba800000, v47
	v_add_f32_e32 v0, v0, v63
	v_fmac_f32_e32 v46, 0xba800000, v62
	v_mul_f32_e32 v63, v47, v47
	v_fmamk_f32 v48, v62, 0xba800000, v48
	v_fmac_f32_e32 v63, v46, v46
	v_fmamk_f32 v49, v62, 0xba800000, v49
	v_fmac_f32_e32 v63, v48, v48
	v_fmac_f32_e32 v63, v49, v49
	v_fmamk_f32 v43, v62, 0xba800000, v43
	v_add_f32_e32 v0, v63, v0
	v_fmac_f32_e32 v42, 0xba800000, v62
	v_mul_f32_e32 v63, v43, v43
	v_fmamk_f32 v44, v62, 0xba800000, v44
	v_fmac_f32_e32 v63, v42, v42
	v_fmamk_f32 v45, v62, 0xba800000, v45
	v_fmac_f32_e32 v63, v44, v44
	v_fmac_f32_e32 v63, v45, v45
	v_add_f32_e32 v0, v63, v0
	ds_bpermute_b32 v63, v56, v0
	s_waitcnt lgkmcnt(0)
	v_add_f32_e32 v0, v0, v63
	ds_bpermute_b32 v63, v57, v0
	s_waitcnt lgkmcnt(0)
	v_add_f32_e32 v0, v0, v63
	ds_bpermute_b32 v63, v58, v0
	s_waitcnt lgkmcnt(0)
	v_add_f32_e32 v0, v0, v63
	ds_bpermute_b32 v63, v59, v0
	s_waitcnt lgkmcnt(0)
	v_add_f32_e32 v0, v0, v63
	ds_bpermute_b32 v63, v60, v0
	s_waitcnt lgkmcnt(0)
	v_add_f32_e32 v0, v0, v63
	ds_bpermute_b32 v63, v61, v0
	s_waitcnt lgkmcnt(0)
	v_add_f32_e32 v0, v0, v63
	v_fmamk_f32 v0, v0, 0x3a800000, v235
	v_cmp_gt_f32_e32 vcc, s2, v0
	v_mul_f32_e32 v63, 0x4f800000, v0
	s_nop 0
	v_cndmask_b32_e32 v0, v0, v63, vcc
	v_sqrt_f32_e32 v63, v0
	s_nop 0
	v_add_u32_e32 v64, -1, v63
	v_fma_f32 v65, -v64, v63, v0
	v_cmp_ge_f32_e64 s[4:5], 0, v65
	v_add_u32_e32 v65, 1, v63
	s_nop 0
	v_cndmask_b32_e64 v64, v63, v64, s[4:5]
	v_fma_f32 v63, -v65, v63, v0
	v_cmp_lt_f32_e64 s[4:5], 0, v63
	s_nop 1
	v_cndmask_b32_e64 v63, v64, v65, s[4:5]
	v_mul_f32_e32 v64, 0x37800000, v63
	v_cndmask_b32_e32 v63, v63, v64, vcc
	v_cmp_class_f32_e32 vcc, v0, v236
	s_nop 1
	v_cndmask_b32_e32 v0, v63, v0, vcc
	v_div_scale_f32 v63, s[4:5], v0, v0, 1.0
	v_rcp_f32_e32 v64, v63
	s_nop 0
	v_fma_f32 v65, -v63, v64, 1.0
	v_fmac_f32_e32 v64, v65, v64
	v_div_scale_f32 v65, vcc, 1.0, v0, 1.0
	v_mul_f32_e32 v66, v65, v64
	v_fma_f32 v67, -v63, v66, v65
	v_fmac_f32_e32 v66, v67, v64
	v_fma_f32 v63, -v63, v66, v65
	v_div_fmas_f32 v63, v63, v64, v66
	v_div_fixup_f32 v0, v63, v0, 1.0
	s_and_saveexec_b64 s[4:5], s[0:1]
	s_cbranch_execz .LBB0_543
	v_readlane_b32 s38, v251, 1
	v_readlane_b32 s39, v251, 2
	v_mul_f32_e32 v62, 0x3a800000, v62
	v_mov_b32_e32 v63, v0
	v_lshl_add_u64 v[64:65], v[50:51], 3, s[38:39]
	global_store_dwordx2 v[64:65], v[62:63], off
	s_branch .LBB0_543
